# P2 stores (HINC, SST) sc1, on top of v102
# baseline (speedup 1.0000x reference)
.LBB0_413:
	s_ashr_i32 s10, s9, 3
	s_and_b32 s11, s6, 0x380
	s_lshl_b32 s13, s10, 10
	s_lshl_b32 s12, s10, 7
	s_or_b32 s10, s13, s11
	s_ashr_i32 s13, s12, 31
	s_lshl_b64 s[12:13], s[12:13], 10
	v_mad_i64_i32 v[18:19], s[18:19], s10, v33, v[4:5]
	v_lshl_add_u64 v[14:15], v[18:19], 0, v[0:1]
	v_lshl_add_u64 v[26:27], v[6:7], 0, s[12:13]
	v_add_co_u32_e32 v28, vcc, s8, v14
	v_lshl_add_u64 v[20:21], v[26:27], 0, v[34:35]
	v_lshl_add_u64 v[16:17], v[18:19], 0, v[8:9]
	v_lshl_add_u64 v[18:19], v[18:19], 0, v[10:11]
	global_load_dwordx4 v[54:57], v[14:15], off
	global_load_dwordx4 v[58:61], v[16:17], off
	v_lshl_add_u64 v[22:23], v[26:27], 0, v[36:37]
	v_lshl_add_u64 v[24:25], v[26:27], 0, v[12:13]
	v_lshl_add_u64 v[26:27], v[26:27], 0, v[38:39]
	v_addc_co_u32_e32 v29, vcc, 0, v15, vcc
	global_load_dwordx4 v[62:65], v[20:21], off
	global_load_dwordx4 v[66:69], v[22:23], off
	global_load_dwordx4 v[70:73], v[24:25], off
	global_load_dwordx4 v[74:77], v[26:27], off
	global_load_dwordx4 v[78:81], v[28:29], off
	global_load_dwordx4 v[82:85], v[18:19], off
	v_lshl_add_u64 v[28:29], v[14:15], 0, s[4:5]
	s_add_i32 s9, s9, s92
	s_add_i32 s6, s6, s7
	s_cmpk_gt_i32 s9, 0xff
	s_waitcnt vmcnt(0)
	ds_write_b128 v44, v[54:57]
	ds_write_b128 v45, v[58:61]
	ds_write_b128 v44, v[78:81] offset:17408
	ds_write_b128 v46, v[82:85]
	ds_write_b128 v44, v[62:65] offset:34816
	ds_write_b128 v45, v[66:69] offset:34816
	ds_write_b128 v44, v[70:73] offset:52224
	ds_write_b128 v46, v[74:77] offset:34816
	s_waitcnt lgkmcnt(0)
	s_barrier
	ds_read_b128 v[54:57], v49 offset:34816
	ds_read_b128 v[58:61], v50
	ds_read_b128 v[62:65], v50 offset:64
	ds_read_b128 v[66:69], v49 offset:34880
	ds_read_b128 v[70:73], v49 offset:39168
	ds_read_b128 v[74:77], v49 offset:39232
	ds_read_b128 v[78:81], v49 offset:43520
	ds_read_b128 v[82:85], v49 offset:43584
	ds_read_b128 v[86:89], v51 offset:34816
	ds_read_b128 v[90:93], v51 offset:34880
	s_waitcnt lgkmcnt(8)
	v_mfma_f32_16x16x32_bf16 v[54:57], v[54:57], v[58:61], 0
	ds_read_b128 v[94:97], v49 offset:52224
	ds_read_b128 v[98:101], v49 offset:52288
	ds_read_b128 v[102:105], v49 offset:56576
	ds_read_b128 v[106:109], v49 offset:56640
	ds_read_b128 v[110:113], v49 offset:60928
	ds_read_b128 v[114:117], v49 offset:60992
	s_waitcnt lgkmcnt(11)
	v_mfma_f32_16x16x32_bf16 v[70:73], v[70:73], v[58:61], 0
	ds_read_b128 v[118:121], v52 offset:34816
	ds_read_b128 v[122:125], v52 offset:34880
	s_waitcnt lgkmcnt(9)
	v_mfma_f32_16x16x32_bf16 v[86:89], v[86:89], v[58:61], 0
	v_mfma_f32_16x16x32_bf16 v[54:57], v[66:69], v[62:65], v[54:57]
	v_mfma_f32_16x16x32_bf16 v[66:69], v[74:77], v[62:65], v[70:73]
	s_waitcnt lgkmcnt(8)
	v_mfma_f32_16x16x32_bf16 v[74:77], v[90:93], v[62:65], v[86:89]
	ds_read_b128 v[90:93], v49 offset:34944
	v_mfma_f32_16x16x32_bf16 v[78:81], v[78:81], v[58:61], 0
	s_waitcnt lgkmcnt(8)
	v_mfma_f32_16x16x32_bf16 v[94:97], v[94:97], v[58:61], 0
	s_waitcnt lgkmcnt(6)
	v_mfma_f32_16x16x32_bf16 v[102:105], v[102:105], v[58:61], 0
	s_waitcnt lgkmcnt(4)
	v_mfma_f32_16x16x32_bf16 v[110:113], v[110:113], v[58:61], 0
	s_waitcnt lgkmcnt(2)
	v_mfma_f32_16x16x32_bf16 v[58:61], v[118:121], v[58:61], 0
	v_mfma_f32_16x16x32_bf16 v[70:73], v[82:85], v[62:65], v[78:81]
	v_mfma_f32_16x16x32_bf16 v[78:81], v[98:101], v[62:65], v[94:97]
	v_mfma_f32_16x16x32_bf16 v[82:85], v[106:109], v[62:65], v[102:105]
	v_mfma_f32_16x16x32_bf16 v[86:89], v[114:117], v[62:65], v[110:113]
	s_waitcnt lgkmcnt(1)
	v_mfma_f32_16x16x32_bf16 v[58:61], v[122:125], v[62:65], v[58:61]
	ds_read_b128 v[62:65], v50 offset:128
	ds_read_b128 v[94:97], v50 offset:192
	ds_read_b128 v[98:101], v49 offset:35008
	s_waitcnt lgkmcnt(2)
	v_mfma_f32_16x16x32_bf16 v[54:57], v[90:93], v[62:65], v[54:57]
	ds_read_b128 v[90:93], v49 offset:39296
	ds_read_b128 v[102:105], v49 offset:39360
	s_waitcnt lgkmcnt(1)
	v_mfma_f32_16x16x32_bf16 v[66:69], v[90:93], v[62:65], v[66:69]
	ds_read_b128 v[90:93], v49 offset:43648
	ds_read_b128 v[106:109], v49 offset:43712
	s_waitcnt lgkmcnt(1)
	v_mfma_f32_16x16x32_bf16 v[70:73], v[90:93], v[62:65], v[70:73]
	ds_read_b128 v[90:93], v51 offset:34944
	ds_read_b128 v[110:113], v51 offset:35008
	s_waitcnt lgkmcnt(1)
	v_mfma_f32_16x16x32_bf16 v[74:77], v[90:93], v[62:65], v[74:77]
	ds_read_b128 v[90:93], v49 offset:52352
	ds_read_b128 v[114:117], v49 offset:52416
	s_waitcnt lgkmcnt(1)
	v_mfma_f32_16x16x32_bf16 v[78:81], v[90:93], v[62:65], v[78:81]
	ds_read_b128 v[90:93], v49 offset:56704
	ds_read_b128 v[118:121], v49 offset:56768
	s_waitcnt lgkmcnt(1)
	v_mfma_f32_16x16x32_bf16 v[82:85], v[90:93], v[62:65], v[82:85]
	ds_read_b128 v[90:93], v49 offset:61056
	ds_read_b128 v[122:125], v49 offset:61120
	s_waitcnt lgkmcnt(1)
	v_mfma_f32_16x16x32_bf16 v[86:89], v[90:93], v[62:65], v[86:89]
	ds_read_b128 v[90:93], v52 offset:34944
	ds_read_b128 v[126:129], v52 offset:35008
	s_waitcnt lgkmcnt(1)
	v_mfma_f32_16x16x32_bf16 v[58:61], v[90:93], v[62:65], v[58:61]
	v_mfma_f32_16x16x32_bf16 v[54:57], v[98:101], v[94:97], v[54:57]
	v_mfma_f32_16x16x32_bf16 v[62:65], v[102:105], v[94:97], v[66:69]
	v_mfma_f32_16x16x32_bf16 v[66:69], v[106:109], v[94:97], v[70:73]
	s_nop 2
	global_load_dwordx4 v[70:73], v[16:17], off offset:256
	v_mfma_f32_16x16x32_bf16 v[74:77], v[110:113], v[94:97], v[74:77]
	global_load_dwordx4 v[90:93], v[14:15], off offset:256
	global_load_dwordx4 v[98:101], v[18:19], off offset:256
	global_load_dwordx4 v[102:105], v[28:29], off offset:256
	v_mfma_f32_16x16x32_bf16 v[78:81], v[114:117], v[94:97], v[78:81]
	global_load_dwordx4 v[106:109], v[22:23], off offset:256
	global_load_dwordx4 v[110:113], v[20:21], off offset:256
	global_load_dwordx4 v[114:117], v[24:25], off offset:256
	v_mfma_f32_16x16x32_bf16 v[82:85], v[118:121], v[94:97], v[82:85]
	global_load_dwordx4 v[118:121], v[26:27], off offset:256
	s_waitcnt lgkmcnt(0)
	s_barrier
	v_mfma_f32_16x16x32_bf16 v[86:89], v[122:125], v[94:97], v[86:89]
	s_waitcnt vmcnt(6)
	ds_write_b128 v44, v[90:93]
	ds_write_b128 v45, v[70:73]
	s_waitcnt vmcnt(4)
	ds_write_b128 v44, v[102:105] offset:17408
	ds_write_b128 v46, v[98:101]
	s_waitcnt vmcnt(2)
	ds_write_b128 v44, v[110:113] offset:34816
	ds_write_b128 v45, v[106:109] offset:34816
	s_waitcnt vmcnt(1)
	ds_write_b128 v44, v[114:117] offset:52224
	s_waitcnt vmcnt(0)
	ds_write_b128 v46, v[118:121] offset:34816
	v_mfma_f32_16x16x32_bf16 v[58:61], v[126:129], v[94:97], v[58:61]
	s_waitcnt lgkmcnt(0)
	s_barrier
	ds_read_b128 v[70:73], v49 offset:34816
	ds_read_b128 v[90:93], v50
	ds_read_b128 v[94:97], v50 offset:64
	ds_read_b128 v[98:101], v49 offset:34880
	s_waitcnt lgkmcnt(2)
	v_mfma_f32_16x16x32_bf16 v[54:57], v[70:73], v[90:93], v[54:57]
	ds_read_b128 v[70:73], v49 offset:39168
	ds_read_b128 v[102:105], v49 offset:39232
	s_waitcnt lgkmcnt(1)
	v_mfma_f32_16x16x32_bf16 v[62:65], v[70:73], v[90:93], v[62:65]
	ds_read_b128 v[70:73], v49 offset:43520
	ds_read_b128 v[106:109], v49 offset:43584
	s_waitcnt lgkmcnt(1)
	v_mfma_f32_16x16x32_bf16 v[66:69], v[70:73], v[90:93], v[66:69]
	ds_read_b128 v[70:73], v51 offset:34816
	ds_read_b128 v[110:113], v51 offset:34880
	s_waitcnt lgkmcnt(1)
	v_mfma_f32_16x16x32_bf16 v[70:73], v[70:73], v[90:93], v[74:77]
	s_nop 2
	ds_read_b128 v[74:77], v49 offset:52224
	ds_read_b128 v[114:117], v49 offset:52288
	s_waitcnt lgkmcnt(1)
	v_mfma_f32_16x16x32_bf16 v[74:77], v[74:77], v[90:93], v[78:81]
	s_nop 2
	ds_read_b128 v[78:81], v49 offset:56576
	ds_read_b128 v[118:121], v49 offset:56640
	s_waitcnt lgkmcnt(1)
	v_mfma_f32_16x16x32_bf16 v[78:81], v[78:81], v[90:93], v[82:85]
	s_nop 2
	ds_read_b128 v[82:85], v49 offset:60928
	ds_read_b128 v[122:125], v49 offset:60992
	s_waitcnt lgkmcnt(1)
	v_mfma_f32_16x16x32_bf16 v[82:85], v[82:85], v[90:93], v[86:89]
	s_nop 2
	ds_read_b128 v[86:89], v52 offset:34816
	ds_read_b128 v[126:129], v52 offset:34880
	s_waitcnt lgkmcnt(1)
	v_mfma_f32_16x16x32_bf16 v[58:61], v[86:89], v[90:93], v[58:61]
	ds_read_b128 v[86:89], v49 offset:34944
	v_mfma_f32_16x16x32_bf16 v[54:57], v[98:101], v[94:97], v[54:57]
	v_mfma_f32_16x16x32_bf16 v[62:65], v[102:105], v[94:97], v[62:65]
	v_mfma_f32_16x16x32_bf16 v[66:69], v[106:109], v[94:97], v[66:69]
	v_mfma_f32_16x16x32_bf16 v[70:73], v[110:113], v[94:97], v[70:73]
	v_mfma_f32_16x16x32_bf16 v[74:77], v[114:117], v[94:97], v[74:77]
	v_mfma_f32_16x16x32_bf16 v[78:81], v[118:121], v[94:97], v[78:81]
	v_mfma_f32_16x16x32_bf16 v[82:85], v[122:125], v[94:97], v[82:85]
	s_waitcnt lgkmcnt(1)
	v_mfma_f32_16x16x32_bf16 v[58:61], v[126:129], v[94:97], v[58:61]
	ds_read_b128 v[90:93], v50 offset:128
	ds_read_b128 v[94:97], v50 offset:192
	ds_read_b128 v[98:101], v49 offset:35008
	s_waitcnt lgkmcnt(2)
	v_mfma_f32_16x16x32_bf16 v[54:57], v[86:89], v[90:93], v[54:57]
	ds_read_b128 v[86:89], v49 offset:39296
	ds_read_b128 v[102:105], v49 offset:39360
	s_waitcnt lgkmcnt(1)
	v_mfma_f32_16x16x32_bf16 v[62:65], v[86:89], v[90:93], v[62:65]
	ds_read_b128 v[86:89], v49 offset:43648
	ds_read_b128 v[106:109], v49 offset:43712
	s_waitcnt lgkmcnt(1)
	v_mfma_f32_16x16x32_bf16 v[66:69], v[86:89], v[90:93], v[66:69]
	ds_read_b128 v[86:89], v51 offset:34944
	ds_read_b128 v[110:113], v51 offset:35008
	s_waitcnt lgkmcnt(1)
	v_mfma_f32_16x16x32_bf16 v[70:73], v[86:89], v[90:93], v[70:73]
	ds_read_b128 v[86:89], v49 offset:52352
	ds_read_b128 v[114:117], v49 offset:52416
	s_waitcnt lgkmcnt(1)
	v_mfma_f32_16x16x32_bf16 v[74:77], v[86:89], v[90:93], v[74:77]
	ds_read_b128 v[86:89], v49 offset:56704
	ds_read_b128 v[118:121], v49 offset:56768
	s_waitcnt lgkmcnt(1)
	v_mfma_f32_16x16x32_bf16 v[78:81], v[86:89], v[90:93], v[78:81]
	ds_read_b128 v[86:89], v49 offset:61056
	ds_read_b128 v[122:125], v49 offset:61120
	s_waitcnt lgkmcnt(1)
	v_mfma_f32_16x16x32_bf16 v[82:85], v[86:89], v[90:93], v[82:85]
	ds_read_b128 v[86:89], v52 offset:34944
	ds_read_b128 v[126:129], v52 offset:35008
	s_waitcnt lgkmcnt(1)
	v_mfma_f32_16x16x32_bf16 v[58:61], v[86:89], v[90:93], v[58:61]
	global_load_dwordx4 v[86:89], v[16:17], off offset:512
	v_mfma_f32_16x16x32_bf16 v[54:57], v[98:101], v[94:97], v[54:57]
	v_mfma_f32_16x16x32_bf16 v[62:65], v[102:105], v[94:97], v[62:65]
	global_load_dwordx4 v[90:93], v[14:15], off offset:512
	global_load_dwordx4 v[98:101], v[18:19], off offset:512
	global_load_dwordx4 v[102:105], v[28:29], off offset:512
	v_mfma_f32_16x16x32_bf16 v[66:69], v[106:109], v[94:97], v[66:69]
	v_mfma_f32_16x16x32_bf16 v[70:73], v[110:113], v[94:97], v[70:73]
	v_mfma_f32_16x16x32_bf16 v[74:77], v[114:117], v[94:97], v[74:77]
	global_load_dwordx4 v[106:109], v[22:23], off offset:512
	global_load_dwordx4 v[110:113], v[20:21], off offset:512
	global_load_dwordx4 v[114:117], v[24:25], off offset:512
	v_mfma_f32_16x16x32_bf16 v[78:81], v[118:121], v[94:97], v[78:81]
	global_load_dwordx4 v[118:121], v[26:27], off offset:512
	s_waitcnt lgkmcnt(0)
	s_barrier
	v_mfma_f32_16x16x32_bf16 v[82:85], v[122:125], v[94:97], v[82:85]
	s_waitcnt vmcnt(6)
	ds_write_b128 v44, v[90:93]
	ds_write_b128 v45, v[86:89]
	s_waitcnt vmcnt(4)
	ds_write_b128 v44, v[102:105] offset:17408
	ds_write_b128 v46, v[98:101]
	s_waitcnt vmcnt(2)
	ds_write_b128 v44, v[110:113] offset:34816
	ds_write_b128 v45, v[106:109] offset:34816
	s_waitcnt vmcnt(1)
	ds_write_b128 v44, v[114:117] offset:52224
	s_waitcnt vmcnt(0)
	ds_write_b128 v46, v[118:121] offset:34816
	v_mfma_f32_16x16x32_bf16 v[58:61], v[126:129], v[94:97], v[58:61]
	s_waitcnt lgkmcnt(0)
	s_barrier
	ds_read_b128 v[86:89], v49 offset:34816
	ds_read_b128 v[90:93], v50
	ds_read_b128 v[94:97], v50 offset:64
	ds_read_b128 v[98:101], v49 offset:34880
	s_waitcnt lgkmcnt(2)
	v_mfma_f32_16x16x32_bf16 v[54:57], v[86:89], v[90:93], v[54:57]
	ds_read_b128 v[86:89], v49 offset:39168
	ds_read_b128 v[102:105], v49 offset:39232
	s_waitcnt lgkmcnt(1)
	v_mfma_f32_16x16x32_bf16 v[62:65], v[86:89], v[90:93], v[62:65]
	ds_read_b128 v[86:89], v49 offset:43520
	ds_read_b128 v[106:109], v49 offset:43584
	s_waitcnt lgkmcnt(1)
	v_mfma_f32_16x16x32_bf16 v[66:69], v[86:89], v[90:93], v[66:69]
	ds_read_b128 v[86:89], v51 offset:34816
	ds_read_b128 v[110:113], v51 offset:34880
	s_waitcnt lgkmcnt(1)
	v_mfma_f32_16x16x32_bf16 v[70:73], v[86:89], v[90:93], v[70:73]
	ds_read_b128 v[86:89], v49 offset:52224
	ds_read_b128 v[114:117], v49 offset:52288
	s_waitcnt lgkmcnt(1)
	v_mfma_f32_16x16x32_bf16 v[74:77], v[86:89], v[90:93], v[74:77]
	ds_read_b128 v[86:89], v49 offset:56576
	ds_read_b128 v[118:121], v49 offset:56640
	s_waitcnt lgkmcnt(1)
	v_mfma_f32_16x16x32_bf16 v[78:81], v[86:89], v[90:93], v[78:81]
	ds_read_b128 v[86:89], v49 offset:60928
	ds_read_b128 v[122:125], v49 offset:60992
	s_waitcnt lgkmcnt(1)
	v_mfma_f32_16x16x32_bf16 v[82:85], v[86:89], v[90:93], v[82:85]
	ds_read_b128 v[86:89], v52 offset:34816
	ds_read_b128 v[126:129], v52 offset:34880
	s_waitcnt lgkmcnt(1)
	v_mfma_f32_16x16x32_bf16 v[58:61], v[86:89], v[90:93], v[58:61]
	ds_read_b128 v[86:89], v49 offset:34944
	v_mfma_f32_16x16x32_bf16 v[54:57], v[98:101], v[94:97], v[54:57]
	v_mfma_f32_16x16x32_bf16 v[62:65], v[102:105], v[94:97], v[62:65]
	v_mfma_f32_16x16x32_bf16 v[66:69], v[106:109], v[94:97], v[66:69]
	v_mfma_f32_16x16x32_bf16 v[70:73], v[110:113], v[94:97], v[70:73]
	v_mfma_f32_16x16x32_bf16 v[74:77], v[114:117], v[94:97], v[74:77]
	v_mfma_f32_16x16x32_bf16 v[78:81], v[118:121], v[94:97], v[78:81]
	v_mfma_f32_16x16x32_bf16 v[82:85], v[122:125], v[94:97], v[82:85]
	s_waitcnt lgkmcnt(1)
	v_mfma_f32_16x16x32_bf16 v[58:61], v[126:129], v[94:97], v[58:61]
	ds_read_b128 v[90:93], v50 offset:128
	ds_read_b128 v[94:97], v50 offset:192
	ds_read_b128 v[98:101], v49 offset:35008
	s_waitcnt lgkmcnt(2)
	v_mfma_f32_16x16x32_bf16 v[54:57], v[86:89], v[90:93], v[54:57]
	ds_read_b128 v[86:89], v49 offset:39296
	ds_read_b128 v[102:105], v49 offset:39360
	s_waitcnt lgkmcnt(1)
	v_mfma_f32_16x16x32_bf16 v[62:65], v[86:89], v[90:93], v[62:65]
	ds_read_b128 v[86:89], v49 offset:43648
	ds_read_b128 v[106:109], v49 offset:43712
	s_waitcnt lgkmcnt(1)
	v_mfma_f32_16x16x32_bf16 v[66:69], v[86:89], v[90:93], v[66:69]
	ds_read_b128 v[86:89], v51 offset:34944
	ds_read_b128 v[110:113], v51 offset:35008
	s_waitcnt lgkmcnt(1)
	v_mfma_f32_16x16x32_bf16 v[70:73], v[86:89], v[90:93], v[70:73]
	ds_read_b128 v[86:89], v49 offset:52352
	ds_read_b128 v[114:117], v49 offset:52416
	s_waitcnt lgkmcnt(1)
	v_mfma_f32_16x16x32_bf16 v[74:77], v[86:89], v[90:93], v[74:77]
	ds_read_b128 v[86:89], v49 offset:56704
	ds_read_b128 v[118:121], v49 offset:56768
	s_waitcnt lgkmcnt(1)
	v_mfma_f32_16x16x32_bf16 v[78:81], v[86:89], v[90:93], v[78:81]
	ds_read_b128 v[86:89], v49 offset:61056
	ds_read_b128 v[122:125], v49 offset:61120
	s_waitcnt lgkmcnt(1)
	v_mfma_f32_16x16x32_bf16 v[82:85], v[86:89], v[90:93], v[82:85]
	ds_read_b128 v[86:89], v52 offset:34944
	ds_read_b128 v[126:129], v52 offset:35008
	s_waitcnt lgkmcnt(1)
	v_mfma_f32_16x16x32_bf16 v[58:61], v[86:89], v[90:93], v[58:61]
	global_load_dwordx4 v[86:89], v[16:17], off offset:768
	v_mfma_f32_16x16x32_bf16 v[54:57], v[98:101], v[94:97], v[54:57]
	global_load_dwordx4 v[14:17], v[14:15], off offset:768
	s_nop 0
	global_load_dwordx4 v[90:93], v[18:19], off offset:768
	global_load_dwordx4 v[98:101], v[28:29], off offset:768
	v_mfma_f32_16x16x32_bf16 v[62:65], v[102:105], v[94:97], v[62:65]
	global_load_dwordx4 v[102:105], v[22:23], off offset:768
	s_nop 0
	global_load_dwordx4 v[18:21], v[20:21], off offset:768
	s_nop 0
	global_load_dwordx4 v[22:25], v[24:25], off offset:768
	s_nop 0
	global_load_dwordx4 v[26:29], v[26:27], off offset:768
	s_waitcnt lgkmcnt(0)
	s_barrier
	s_waitcnt vmcnt(6)
	ds_write_b128 v44, v[14:17]
	ds_write_b128 v45, v[86:89]
	s_waitcnt vmcnt(4)
	ds_write_b128 v44, v[98:101] offset:17408
	ds_write_b128 v46, v[90:93]
	s_waitcnt vmcnt(2)
	ds_write_b128 v44, v[18:21] offset:34816
	ds_write_b128 v45, v[102:105] offset:34816
	s_waitcnt vmcnt(1)
	ds_write_b128 v44, v[22:25] offset:52224
	s_waitcnt vmcnt(0)
	ds_write_b128 v46, v[26:29] offset:34816
	s_waitcnt lgkmcnt(0)
	s_barrier
	ds_read_b128 v[14:17], v49 offset:34816
	ds_read_b128 v[18:21], v50
	ds_read_b128 v[22:25], v50 offset:64
	ds_read_b128 v[26:29], v49 offset:34880
	s_waitcnt lgkmcnt(2)
	v_mfma_f32_16x16x32_bf16 v[14:17], v[14:17], v[18:21], v[54:57]
	s_nop 2
	ds_read_b128 v[54:57], v49 offset:39168
	ds_read_b128 v[86:89], v49 offset:39232
	v_mfma_f32_16x16x32_bf16 v[66:69], v[106:109], v[94:97], v[66:69]
	s_waitcnt lgkmcnt(1)
	v_mfma_f32_16x16x32_bf16 v[54:57], v[54:57], v[18:21], v[62:65]
	s_nop 2
	ds_read_b128 v[62:65], v49 offset:43520
	ds_read_b128 v[90:93], v49 offset:43584
	v_mfma_f32_16x16x32_bf16 v[70:73], v[110:113], v[94:97], v[70:73]
	v_mfma_f32_16x16x32_bf16 v[74:77], v[114:117], v[94:97], v[74:77]
	v_mfma_f32_16x16x32_bf16 v[78:81], v[118:121], v[94:97], v[78:81]
	v_mfma_f32_16x16x32_bf16 v[82:85], v[122:125], v[94:97], v[82:85]
	v_mfma_f32_16x16x32_bf16 v[58:61], v[126:129], v[94:97], v[58:61]
	s_waitcnt lgkmcnt(1)
	v_mfma_f32_16x16x32_bf16 v[62:65], v[62:65], v[18:21], v[66:69]
	s_nop 2
	ds_read_b128 v[66:69], v51 offset:34816
	ds_read_b128 v[94:97], v51 offset:34880
	s_waitcnt lgkmcnt(1)
	v_mfma_f32_16x16x32_bf16 v[66:69], v[66:69], v[18:21], v[70:73]
	s_nop 2
	ds_read_b128 v[70:73], v49 offset:52224
	ds_read_b128 v[98:101], v49 offset:52288
	s_waitcnt lgkmcnt(1)
	v_mfma_f32_16x16x32_bf16 v[70:73], v[70:73], v[18:21], v[74:77]
	s_nop 2
	ds_read_b128 v[74:77], v49 offset:56576
	ds_read_b128 v[102:105], v49 offset:56640
	s_waitcnt lgkmcnt(1)
	v_mfma_f32_16x16x32_bf16 v[74:77], v[74:77], v[18:21], v[78:81]
	s_nop 2
	ds_read_b128 v[78:81], v49 offset:60928
	ds_read_b128 v[106:109], v49 offset:60992
	s_waitcnt lgkmcnt(1)
	v_mfma_f32_16x16x32_bf16 v[78:81], v[78:81], v[18:21], v[82:85]
	s_nop 2
	ds_read_b128 v[82:85], v52 offset:34816
	ds_read_b128 v[110:113], v52 offset:34880
	s_waitcnt lgkmcnt(1)
	v_mfma_f32_16x16x32_bf16 v[18:21], v[82:85], v[18:21], v[58:61]
	v_mfma_f32_16x16x32_bf16 v[58:61], v[94:97], v[22:25], v[66:69]
	v_mfma_f32_16x16x32_bf16 v[66:69], v[102:105], v[22:25], v[74:77]
	s_nop 2
	ds_read_b128 v[74:77], v49 offset:34944
	v_mfma_f32_16x16x32_bf16 v[14:17], v[26:29], v[22:25], v[14:17]
	v_mfma_f32_16x16x32_bf16 v[26:29], v[86:89], v[22:25], v[54:57]
	v_mfma_f32_16x16x32_bf16 v[54:57], v[90:93], v[22:25], v[62:65]
	v_mfma_f32_16x16x32_bf16 v[62:65], v[98:101], v[22:25], v[70:73]
	v_mfma_f32_16x16x32_bf16 v[70:73], v[106:109], v[22:25], v[78:81]
	s_waitcnt lgkmcnt(1)
	v_mfma_f32_16x16x32_bf16 v[18:21], v[110:113], v[22:25], v[18:21]
	ds_read_b128 v[22:25], v50 offset:128
	ds_read_b128 v[78:81], v50 offset:192
	ds_read_b128 v[82:85], v49 offset:35008
	s_waitcnt lgkmcnt(2)
	v_mfma_f32_16x16x32_bf16 v[14:17], v[74:77], v[22:25], v[14:17]
	ds_read_b128 v[74:77], v49 offset:39296
	ds_read_b128 v[86:89], v49 offset:39360
	s_waitcnt lgkmcnt(1)
	v_mfma_f32_16x16x32_bf16 v[26:29], v[74:77], v[22:25], v[26:29]
	ds_read_b128 v[74:77], v49 offset:43648
	ds_read_b128 v[90:93], v49 offset:43712
	s_waitcnt lgkmcnt(1)
	v_mfma_f32_16x16x32_bf16 v[54:57], v[74:77], v[22:25], v[54:57]
	ds_read_b128 v[74:77], v51 offset:34944
	ds_read_b128 v[94:97], v51 offset:35008
	s_waitcnt lgkmcnt(1)
	v_mfma_f32_16x16x32_bf16 v[58:61], v[74:77], v[22:25], v[58:61]
	ds_read_b128 v[74:77], v49 offset:52352
	ds_read_b128 v[98:101], v49 offset:52416
	s_waitcnt lgkmcnt(1)
	v_mfma_f32_16x16x32_bf16 v[62:65], v[74:77], v[22:25], v[62:65]
	ds_read_b128 v[74:77], v49 offset:56704
	ds_read_b128 v[102:105], v49 offset:56768
	s_waitcnt lgkmcnt(1)
	v_mfma_f32_16x16x32_bf16 v[66:69], v[74:77], v[22:25], v[66:69]
	ds_read_b128 v[74:77], v49 offset:61056
	ds_read_b128 v[106:109], v49 offset:61120
	s_waitcnt lgkmcnt(1)
	v_mfma_f32_16x16x32_bf16 v[70:73], v[74:77], v[22:25], v[70:73]
	ds_read_b128 v[74:77], v52 offset:34944
	ds_read_b128 v[110:113], v52 offset:35008
	s_waitcnt lgkmcnt(0)
	s_barrier
	v_mfma_f32_16x16x32_bf16 v[18:21], v[74:77], v[22:25], v[18:21]
	v_add_u32_e32 v74, s10, v31
	v_ashrrev_i32_e32 v75, 31, v74
	v_mfma_f32_16x16x32_bf16 v[14:17], v[82:85], v[78:81], v[14:17]
	v_mfma_f32_16x16x32_bf16 v[22:25], v[86:89], v[78:81], v[26:29]
	v_mfma_f32_16x16x32_bf16 v[26:29], v[90:93], v[78:81], v[54:57]
	v_mfma_f32_16x16x32_bf16 v[54:57], v[94:97], v[78:81], v[58:61]
	v_mfma_f32_16x16x32_bf16 v[58:61], v[98:101], v[78:81], v[62:65]
	v_mfma_f32_16x16x32_bf16 v[62:65], v[102:105], v[78:81], v[66:69]
	s_nop 2
	v_lshlrev_b64 v[66:67], 9, v[74:75]
	v_lshl_add_u64 v[74:75], v[2:3], 0, v[66:67]
	v_mfma_f32_16x16x32_bf16 v[66:69], v[106:109], v[78:81], v[70:73]
	v_mfma_f32_16x16x32_bf16 v[18:21], v[110:113], v[78:81], v[18:21]
	global_store_dwordx4 v[74:75], v[14:17], off sc1
	global_store_dwordx4 v[74:75], v[22:25], off offset:64 sc1
	global_store_dwordx4 v[74:75], v[26:29], off offset:128 sc1
	global_store_dwordx4 v[74:75], v[54:57], off offset:192 sc1
	global_store_dwordx4 v[74:75], v[58:61], off offset:256 sc1
	global_store_dwordx4 v[74:75], v[62:65], off offset:320 sc1
	s_nop 0
	global_store_dwordx4 v[74:75], v[66:69], off offset:384 sc1
	global_store_dwordx4 v[74:75], v[18:21], off offset:448 sc1
	s_cbranch_scc0 .LBB0_413

.LBB0_416:
	ds_read_b64_tr_b16 v[64:65], v48
	ds_read_b64_tr_b16 v[66:67], v48 offset:1088
	s_waitcnt lgkmcnt(0)
	ds_read_b64_tr_b16 v[96:97], v52
	ds_read_b64_tr_b16 v[98:99], v52 offset:1088
	ds_read_b64_tr_b16 v[92:93], v52 offset:32
	ds_read_b64_tr_b16 v[94:95], v52 offset:1120
	ds_read_b64_tr_b16 v[88:89], v52 offset:64
	ds_read_b64_tr_b16 v[90:91], v52 offset:1152
	ds_read_b64_tr_b16 v[84:85], v52 offset:96
	ds_read_b64_tr_b16 v[86:87], v52 offset:1184
	ds_read_b64_tr_b16 v[80:81], v52 offset:128
	ds_read_b64_tr_b16 v[82:83], v52 offset:1216
	ds_read_b64_tr_b16 v[76:77], v52 offset:160
	ds_read_b64_tr_b16 v[78:79], v52 offset:1248
	ds_read_b64_tr_b16 v[72:73], v52 offset:192
	ds_read_b64_tr_b16 v[74:75], v52 offset:1280
	ds_read_b64_tr_b16 v[68:69], v52 offset:224
	ds_read_b64_tr_b16 v[70:71], v52 offset:1312
	s_waitcnt lgkmcnt(0)
	s_add_i32 s8, s8, s9
	v_mfma_f32_16x16x32_bf16 v[96:99], v[96:99], v[64:67], 0
	s_add_i32 s10, s10, s11
	s_andn2_b64 vcc, exec, s[6:7]
	v_mfma_f32_16x16x32_bf16 v[92:95], v[92:95], v[64:67], 0
	v_mfma_f32_16x16x32_bf16 v[88:91], v[88:91], v[64:67], 0
	v_mfma_f32_16x16x32_bf16 v[84:87], v[84:87], v[64:67], 0
	v_mfma_f32_16x16x32_bf16 v[80:83], v[80:83], v[64:67], 0
	v_mfma_f32_16x16x32_bf16 v[76:79], v[76:79], v[64:67], 0
	v_mfma_f32_16x16x32_bf16 v[72:75], v[72:75], v[64:67], 0
	v_mfma_f32_16x16x32_bf16 v[64:67], v[68:71], v[64:67], 0
	ds_read_b64_tr_b16 v[68:69], v53
	ds_read_b64_tr_b16 v[70:71], v53 offset:1088
	s_waitcnt lgkmcnt(0)
	ds_read_b64_tr_b16 v[128:129], v54
	ds_read_b64_tr_b16 v[130:131], v54 offset:1088
	ds_read_b64_tr_b16 v[124:125], v54 offset:32
	ds_read_b64_tr_b16 v[126:127], v54 offset:1120
	ds_read_b64_tr_b16 v[120:121], v54 offset:64
	ds_read_b64_tr_b16 v[122:123], v54 offset:1152
	ds_read_b64_tr_b16 v[116:117], v54 offset:96
	ds_read_b64_tr_b16 v[118:119], v54 offset:1184
	ds_read_b64_tr_b16 v[112:113], v54 offset:128
	ds_read_b64_tr_b16 v[114:115], v54 offset:1216
	ds_read_b64_tr_b16 v[108:109], v54 offset:160
	ds_read_b64_tr_b16 v[110:111], v54 offset:1248
	ds_read_b64_tr_b16 v[104:105], v54 offset:192
	ds_read_b64_tr_b16 v[106:107], v54 offset:1280
	ds_read_b64_tr_b16 v[100:101], v54 offset:224
	ds_read_b64_tr_b16 v[102:103], v54 offset:1312
	s_waitcnt lgkmcnt(0)
	s_nop 0
	v_mfma_f32_16x16x32_bf16 v[96:99], v[128:131], v[68:71], v[96:99]
	v_mfma_f32_16x16x32_bf16 v[92:95], v[124:127], v[68:71], v[92:95]
	v_mfma_f32_16x16x32_bf16 v[88:91], v[120:123], v[68:71], v[88:91]
	v_mfma_f32_16x16x32_bf16 v[84:87], v[116:119], v[68:71], v[84:87]
	v_mfma_f32_16x16x32_bf16 v[80:83], v[112:115], v[68:71], v[80:83]
	v_mfma_f32_16x16x32_bf16 v[76:79], v[108:111], v[68:71], v[76:79]
	v_mfma_f32_16x16x32_bf16 v[72:75], v[104:107], v[68:71], v[72:75]
	v_mfma_f32_16x16x32_bf16 v[64:67], v[100:103], v[68:71], v[64:67]
	ds_read_b64_tr_b16 v[68:69], v55
	ds_read_b64_tr_b16 v[70:71], v55 offset:1088
	s_waitcnt lgkmcnt(0)
	ds_read_b64_tr_b16 v[128:129], v56
	ds_read_b64_tr_b16 v[130:131], v56 offset:1088
	ds_read_b64_tr_b16 v[124:125], v56 offset:32
	ds_read_b64_tr_b16 v[126:127], v56 offset:1120
	ds_read_b64_tr_b16 v[120:121], v56 offset:64
	ds_read_b64_tr_b16 v[122:123], v56 offset:1152
	ds_read_b64_tr_b16 v[116:117], v56 offset:96
	ds_read_b64_tr_b16 v[118:119], v56 offset:1184
	ds_read_b64_tr_b16 v[112:113], v56 offset:128
	ds_read_b64_tr_b16 v[114:115], v56 offset:1216
	ds_read_b64_tr_b16 v[108:109], v56 offset:160
	ds_read_b64_tr_b16 v[110:111], v56 offset:1248
	ds_read_b64_tr_b16 v[104:105], v56 offset:192
	ds_read_b64_tr_b16 v[106:107], v56 offset:1280
	ds_read_b64_tr_b16 v[100:101], v56 offset:224
	ds_read_b64_tr_b16 v[102:103], v56 offset:1312
	s_waitcnt lgkmcnt(0)
	s_nop 0
	v_mfma_f32_16x16x32_bf16 v[96:99], v[128:131], v[68:71], v[96:99]
	v_mfma_f32_16x16x32_bf16 v[92:95], v[124:127], v[68:71], v[92:95]
	v_mfma_f32_16x16x32_bf16 v[88:91], v[120:123], v[68:71], v[88:91]
	v_mfma_f32_16x16x32_bf16 v[84:87], v[116:119], v[68:71], v[84:87]
	v_mfma_f32_16x16x32_bf16 v[80:83], v[112:115], v[68:71], v[80:83]
	v_mfma_f32_16x16x32_bf16 v[76:79], v[108:111], v[68:71], v[76:79]
	v_mfma_f32_16x16x32_bf16 v[72:75], v[104:107], v[68:71], v[72:75]
	ds_read_b64_tr_b16 v[104:105], v57
	ds_read_b64_tr_b16 v[106:107], v57 offset:1088
	s_waitcnt lgkmcnt(0)
	v_mfma_f32_16x16x32_bf16 v[64:67], v[100:103], v[68:71], v[64:67]
	ds_read_b64_tr_b16 v[128:129], v58
	ds_read_b64_tr_b16 v[130:131], v58 offset:1088
	ds_read_b64_tr_b16 v[124:125], v58 offset:32
	ds_read_b64_tr_b16 v[126:127], v58 offset:1120
	ds_read_b64_tr_b16 v[120:121], v58 offset:64
	ds_read_b64_tr_b16 v[122:123], v58 offset:1152
	ds_read_b64_tr_b16 v[116:117], v58 offset:96
	ds_read_b64_tr_b16 v[118:119], v58 offset:1184
	ds_read_b64_tr_b16 v[112:113], v58 offset:128
	ds_read_b64_tr_b16 v[114:115], v58 offset:1216
	ds_read_b64_tr_b16 v[108:109], v58 offset:160
	ds_read_b64_tr_b16 v[110:111], v58 offset:1248
	ds_read_b64_tr_b16 v[100:101], v58 offset:192
	ds_read_b64_tr_b16 v[102:103], v58 offset:1280
	ds_read_b64_tr_b16 v[68:69], v58 offset:224
	ds_read_b64_tr_b16 v[70:71], v58 offset:1312
	s_waitcnt lgkmcnt(0)
	s_nop 0
	v_mfma_f32_16x16x32_bf16 v[96:99], v[128:131], v[104:107], v[96:99]
	v_mfma_f32_16x16x32_bf16 v[92:95], v[124:127], v[104:107], v[92:95]
	v_mfma_f32_16x16x32_bf16 v[88:91], v[120:123], v[104:107], v[88:91]
	s_nop 5
	v_cvt_pk_bf16_f32 v96, v96, v97
	v_cvt_pk_bf16_f32 v97, v98, v99
	v_cvt_pk_bf16_f32 v92, v92, v93
	v_mfma_f32_16x16x32_bf16 v[84:87], v[116:119], v[104:107], v[84:87]
	v_cvt_pk_bf16_f32 v93, v94, v95
	v_cvt_pk_bf16_f32 v88, v88, v89
	v_cvt_pk_bf16_f32 v89, v90, v91
	v_mfma_f32_16x16x32_bf16 v[80:83], v[112:115], v[104:107], v[80:83]
	global_store_dwordx2 v[40:41], v[96:97], off offset:-128 sc1
	s_nop 2
	v_cvt_pk_bf16_f32 v84, v84, v85
	v_cvt_pk_bf16_f32 v85, v86, v87
	v_mfma_f32_16x16x32_bf16 v[76:79], v[108:111], v[104:107], v[76:79]
	global_store_dwordx2 v[40:41], v[92:93], off offset:-96 sc1
	v_cvt_pk_bf16_f32 v80, v80, v81
	v_cvt_pk_bf16_f32 v81, v82, v83
	v_mfma_f32_16x16x32_bf16 v[72:75], v[100:103], v[104:107], v[72:75]
	global_store_dwordx2 v[40:41], v[88:89], off offset:-64 sc1
	s_nop 2
	v_cvt_pk_bf16_f32 v76, v76, v77
	v_cvt_pk_bf16_f32 v77, v78, v79
	v_mfma_f32_16x16x32_bf16 v[64:67], v[68:71], v[104:107], v[64:67]
	global_store_dwordx2 v[40:41], v[84:85], off offset:-32 sc1
	v_cvt_pk_bf16_f32 v72, v72, v73
	v_cvt_pk_bf16_f32 v73, v74, v75
	global_store_dwordx2 v[40:41], v[80:81], off sc1
	global_store_dwordx2 v[40:41], v[76:77], off offset:32 sc1
	s_nop 2
	v_cvt_pk_bf16_f32 v64, v64, v65
	v_cvt_pk_bf16_f32 v65, v66, v67
	global_store_dwordx2 v[40:41], v[72:73], off offset:64 sc1
	global_store_dwordx2 v[40:41], v[64:65], off offset:96 sc1
	v_lshl_add_u64 v[40:41], v[40:41], 0, s[4:5]
	s_barrier
	s_cbranch_vccz .LBB0_419
